# v63 plus instruction-fetch warm-up: at kernel entry every thread reads its 128-byte slice of the kernel's own code (PC-relative, discarded) so later instruction-cache misses hit L2 / the memory-side c
# speedup vs baseline: 1.0086x; 1.0074x over previous
_Z10fwd_kernel4Args:
	s_load_dwordx16 s[56:71], s[0:1], 0x0
	s_load_dwordx16 s[4:19], s[0:1], 0x40
	s_load_dwordx16 s[40:55], s[0:1], 0xc0
	s_load_dword s33, s[0:1], 0x100
	v_lshl_add_u32 v24, v0, 2, 0
	s_mov_b32 s38, s2
	s_waitcnt lgkmcnt(0)
	v_writelane_b32 v242, s4, 0
	v_mov_b32_e32 v1, v0
	v_readfirstlane_b32 s3, v0
	s_getpc_b64 s[98:99]
	v_lshlrev_b32_e32 v232, 7, v0
	global_load_dword v233, v232, s[98:99]
	v_add_u32_e32 v234, 0x10000, v232
	global_load_dword v235, v234, s[98:99]
	v_add_u32_e32 v234, 0x20000, v232
	v_cmp_gt_u32_e32 vcc, 0x170, v0
	s_and_saveexec_b64 s[100:101], vcc
	global_load_dword v236, v234, s[98:99]
	s_mov_b64 exec, s[100:101]
	v_writelane_b32 v242, s5, 1
	v_writelane_b32 v242, s6, 2
	v_writelane_b32 v242, s7, 3
	v_writelane_b32 v242, s8, 4
	v_writelane_b32 v242, s9, 5
	v_writelane_b32 v242, s10, 6
	v_writelane_b32 v242, s11, 7
	v_writelane_b32 v242, s12, 8
	v_writelane_b32 v242, s13, 9
	v_writelane_b32 v242, s14, 10
	v_writelane_b32 v242, s15, 11
	v_writelane_b32 v242, s16, 12
	v_writelane_b32 v242, s17, 13
	v_writelane_b32 v242, s18, 14
	v_writelane_b32 v242, s19, 15
	s_load_dwordx16 s[4:19], s[0:1], 0x80
	v_add_u32_e32 v2, 0x21800, v24
	v_mov_b32_e32 v3, 0
	s_waitcnt lgkmcnt(0)
	v_writelane_b32 v242, s4, 16
	s_nop 1
	v_writelane_b32 v242, s5, 17
	v_writelane_b32 v242, s6, 18
	v_writelane_b32 v242, s7, 19
	v_writelane_b32 v242, s8, 20
	v_writelane_b32 v242, s9, 21
	v_writelane_b32 v242, s10, 22
	v_writelane_b32 v242, s11, 23
	v_writelane_b32 v242, s12, 24
	v_writelane_b32 v242, s13, 25
	v_writelane_b32 v242, s14, 26
	v_writelane_b32 v242, s15, 27
	v_writelane_b32 v242, s16, 28
	v_writelane_b32 v242, s17, 29
	v_writelane_b32 v242, s18, 30
	v_writelane_b32 v242, s19, 31
	s_add_u32 s4, s0, 0x100
	s_addc_u32 s5, s1, 0
	v_writelane_b32 v242, s4, 32
	s_mov_b32 s0, 0
	s_mov_b32 s1, 1
	v_writelane_b32 v242, s5, 33
	s_mov_b64 s[4:5], 0
	s_mov_b32 s6, s0
	s_branch .LBB0_2
